# v8 + non-temporal policy on attention Q loads and AO stores (read-once / write-once data)
# speedup vs baseline: 1.0046x; 1.0046x over previous
; #define ATT_WAIT_BAR(N) asm volatile("s_waitcnt vmcnt(" #N ") lgkmcnt(0)\n\ts_barrier" ::: "memory")
; #define DMA_T(t, s) do { const long go_ = (long)(t) * KVBLK * PITCH; const unsigned sd_ = (unsigned)__builtin_amdgcn_readfirstlane(pdst + (s) * SLOTB); \
;         glds16(ksrc + go_, sd_); glds16(ksrc + go_ + 64, sd_ + OFF_K1); glds16(vsrc + go_, sd_ + OFF_V); glds16(vsrc + go_ + 64, sd_ + OFF_V + 8192); } while (0)
; __device__ __forceinline__ void attn_unit(const int b, const int h, const int qb, const bf16_t* Q, const bf16_t* K, const bf16_t* V, bf16_t* O, ATT_LAS char* shm, const float lam) {
;     const int tid = threadIdx.x, lane = tid & 63, r32 = lane & 31, hi = lane >> 5; const int wid = __builtin_amdgcn_readfirstlane(tid >> 6), sub = wid >> 2, w4 = wid & 3;
;     const long rowbase = (long)b * SEQ; const int q0 = qb * QB2;
;     const bf16_t* Qw = Q + (rowbase + q0 + w4 * QBLK) * PITCH + h * 128 + sub * 64;
;     const bf16_t* Kh = K + rowbase * PITCH + h * 128; const bf16_t* Vh = V + rowbase * PITCH + h * 128;
;     const unsigned lds0 = (unsigned)(uintptr_t)shm;
;     const bf16_t* ksrc = Kh + (long)lane * PITCH + wid * 8;
;     const bf16_t* vsrc = Vh + (long)(16 * (wid & 3) + (lane >> 2)) * PITCH + (wid >> 2) * 32 + (lane & 3) * 8;
;     const unsigned pdst = lds0 + wid * 1024;
;     ...
;     const lds_cptr kp0 = (lds_cptr)shm + sub * OFF_K1 + hi * 1024 + r32 * 16;
;     const lds_cptr vp0 = (lds_cptr)shm + OFF_V + ((lane >> 4) & 1) * 32 + (lane & 3) * 8 + (4 * hi + ((lane & 15) >> 2)) * 64;
;     const int NT = (q0 + QB2) / KVBLK;
;     const int mylast = q0 / KVBLK + (w4 >> 1);
;     DMA_T(0, 0); DMA_T(1, 1);
;     bf16x8 qr[4];
; #pragma unroll
;     for (int d0 = 0; d0 < 4; ++d0) qr[d0] = *reinterpret_cast<const bf16x8*>(&Qw[(long)r32 * PITCH + d0 * 16 + hi * 8]);
;     asm volatile("" : "+v"(qr[0]), "+v"(qr[1]), "+v"(qr[2]), "+v"(qr[3]));
;     f32x16 o[4]; o[0] = f32x16{}; o[1] = f32x16{}; o[2] = f32x16{}; o[3] = f32x16{};
;     float l_reg = 0.f;
;     int slot = 0, slot2 = 2;
;     for (int t = 0; t < NT; ++t) {
;         if (t + 1 < NT) { ATT_WAIT_BAR(4); } else { ATT_WAIT_BAR(0); }
;         if (t + 2 < NT) DMA_T(t + 2, slot2);
.LBB0_466:
	s_bitcmp0_b32 s34, 0
	v_readfirstlane_b32 s3, v164
	s_cselect_b32 s44, s6, s7
	s_bfe_u32 s31, s3, 0x20006
	s_lshl_b32 s30, s31, 14
	s_lshl_b32 s16, s44, 16
	s_or_b32 s16, s30, s16
	s_or_b32 s26, s0, s16
	s_mov_b32 s27, s1
	s_lshr_b32 s45, s3, 6
	s_lshr_b32 s39, s3, 8
	s_lshl_b32 s46, s44, 7
	s_lshl_b64 s[26:27], s[26:27], 1
	s_add_u32 s36, s85, s26
	s_addc_u32 s37, s86, s27
	s_lshl_b32 s35, s34, 7
	s_lshl_b32 s16, s34, 8
	s_add_u32 s38, s36, s16
	s_addc_u32 s41, s37, 0
	s_lshl_b32 s36, s39, 6
	s_lshl_b32 s40, s39, 7
	s_add_u32 s40, s38, s40
	s_addc_u32 s41, s41, 0
	s_add_u32 s42, s8, s16
	s_addc_u32 s43, s9, 0
	s_lshl_b32 s38, s31, 13
	v_or_b32_e32 v0, s38, v152
	v_lshl_add_u64 v[2:3], v[114:115], 0, s[16:17]
	s_lshl_b32 s16, s45, 13
	v_lshlrev_b32_e32 v0, 1, v0
	s_lshl_b32 s31, s45, 10
	s_mov_b32 s37, s17
	v_lshl_add_u64 v[2:3], v[2:3], 0, s[16:17]
	v_lshl_add_u64 v[4:5], s[42:43], 0, v[0:1]
	s_add_i32 s31, s31, 0
	s_mov_b32 s16, m0
	s_mov_b32 m0, s31
	s_nop 0
	global_load_lds_dwordx4 v[2:3], off
	s_mov_b32 m0, s16
	v_lshl_add_u64 v[4:5], v[4:5], 0, s[36:37]
	v_mov_b32_e32 v121, v1
	v_lshl_add_u64 v[6:7], v[2:3], 0, s[18:19]
	s_add_i32 s16, s31, 0x2000
	s_mov_b32 s42, m0
	s_mov_b32 m0, s16
	s_nop 0
	global_load_lds_dwordx4 v[6:7], off
	s_mov_b32 m0, s42
	v_lshl_add_u64 v[4:5], v[4:5], 0, v[120:121]
	s_add_i32 s16, s31, 0x4000
	s_mov_b32 s42, m0
	s_mov_b32 m0, s16
	s_nop 0
	global_load_lds_dwordx4 v[4:5], off
	s_mov_b32 m0, s42
	v_lshl_add_u64 v[6:7], v[4:5], 0, s[18:19]
	s_add_i32 s16, s31, 0x6000
	s_mov_b32 s42, m0
	s_mov_b32 m0, s16
	s_nop 0
	global_load_lds_dwordx4 v[6:7], off
	s_mov_b32 m0, s42
	s_add_i32 s16, s31, 0x8000
	v_lshl_add_u64 v[6:7], v[2:3], 0, s[20:21]
	s_mov_b32 s42, m0
	s_mov_b32 m0, s16
	s_nop 0
	global_load_lds_dwordx4 v[6:7], off
	s_mov_b32 m0, s42
	v_lshl_add_u64 v[2:3], v[2:3], 0, s[22:23]
	s_add_i32 s16, s31, 0xa000
	s_mov_b32 s42, m0
	s_mov_b32 m0, s16
	s_nop 0
	global_load_lds_dwordx4 v[2:3], off
	s_mov_b32 m0, s42
	v_lshl_add_u64 v[2:3], v[4:5], 0, s[20:21]
	s_add_i32 s16, s31, 0xc000
	s_mov_b32 s42, m0
	s_mov_b32 m0, s16
	s_nop 0
	global_load_lds_dwordx4 v[2:3], off
	s_mov_b32 m0, s42
	v_lshl_add_u64 v[2:3], v[4:5], 0, s[22:23]
	s_add_i32 s16, s31, 0xe000
	s_mov_b32 s42, m0
	s_mov_b32 m0, s16
	s_nop 0
	global_load_lds_dwordx4 v[2:3], off
	s_mov_b32 m0, s42
	global_load_dwordx4 v[98:101], v213, s[40:41] offset:96 nt
	global_load_dwordx4 v[102:105], v213, s[40:41] offset:64 nt
	global_load_dwordx4 v[106:109], v213, s[40:41] offset:32 nt
	global_load_dwordx4 v[110:113], v213, s[40:41] nt
	v_mov_b32_e32 v14, v1
	v_mov_b32_e32 v15, v1
	v_mov_b32_e32 v2, v1
	v_mov_b32_e32 v3, v1
	v_mov_b32_e32 v4, v1
	v_mov_b32_e32 v5, v1
	v_mov_b32_e32 v6, v1
	v_mov_b32_e32 v7, v1
	v_mov_b32_e32 v8, v1
	v_mov_b32_e32 v9, v1
	v_mov_b32_e32 v10, v1
	v_mov_b32_e32 v11, v1
	v_mov_b32_e32 v12, v1
	v_mov_b32_e32 v13, v1
	s_addk_i32 s46, 0x80
	s_bfe_u32 s16, s45, 0x10001
	s_lshl_b32 s42, s44, 1
	s_lshr_b32 s44, s3, 2
	v_lshl_add_u64 v[16:17], s[36:37], 0, v[0:1]
	v_mov_b32_e32 v0, v1
	v_mov_b64_e32 v[64:65], v[14:15]
	v_mov_b64_e32 v[48:49], v[14:15]
	v_mov_b64_e32 v[32:33], v[14:15]
	s_lshr_b32 s43, s46, 6
	s_or_b32 s42, s16, s42
	s_lshr_b32 s16, s3, 6
	s_lshl_b32 s16, s16, 13
	v_lshl_add_u64 v[142:143], v[118:119], 0, v[16:17]
	v_mov_b64_e32 v[62:63], v[12:13]
	v_mov_b64_e32 v[60:61], v[10:11]
	v_mov_b64_e32 v[58:59], v[8:9]
	v_mov_b64_e32 v[56:57], v[6:7]
	v_mov_b64_e32 v[54:55], v[4:5]
	v_mov_b64_e32 v[52:53], v[2:3]
	v_mov_b64_e32 v[50:51], v[0:1]
	v_mov_b64_e32 v[46:47], v[12:13]
	v_mov_b64_e32 v[44:45], v[10:11]
	v_mov_b64_e32 v[42:43], v[8:9]
	v_mov_b64_e32 v[40:41], v[6:7]
	v_mov_b64_e32 v[38:39], v[4:5]
	v_mov_b64_e32 v[36:37], v[2:3]
	v_mov_b64_e32 v[34:35], v[0:1]
	v_mov_b64_e32 v[30:31], v[12:13]
	v_mov_b64_e32 v[28:29], v[10:11]
	v_mov_b64_e32 v[26:27], v[8:9]
	v_mov_b64_e32 v[24:25], v[6:7]
	v_mov_b64_e32 v[22:23], v[4:5]
	v_mov_b64_e32 v[20:21], v[2:3]
	v_mov_b64_e32 v[18:19], v[0:1]
	v_mov_b64_e32 v[16:17], v[14:15]
	v_mov_b32_e32 v121, 0
	s_mov_b32 s40, 0
	s_mov_b32 s41, 2
	v_lshl_add_u32 v123, s39, 13, v154
	s_add_i32 s44, s43, -2
	s_add_i32 s45, s43, -1
	v_lshl_add_u64 v[140:141], v[116:117], 0, s[16:17]
	v_mov_b64_e32 v[14:15], v[12:13]
	v_mov_b64_e32 v[12:13], v[10:11]
	v_mov_b64_e32 v[10:11], v[8:9]
	v_mov_b64_e32 v[8:9], v[6:7]
	v_mov_b64_e32 v[6:7], v[4:5]
	v_mov_b64_e32 v[4:5], v[2:3]
	v_mov_b64_e32 v[2:3], v[0:1]
	s_mov_b32 s16, 0
	s_waitcnt vmcnt(0)
	v_and_b32_e32 v0, 63, v164
	v_and_b32_e32 v125, 31, v0
	v_lshlrev_b32_e32 v123, 7, v125
	v_lshl_add_u32 v123, s39, 13, v123
	v_lshrrev_b32_e32 v125, 5, v0
	v_bfe_u32 v162, v0, 1, 1
	v_xor_b32_e32 v125, v125, v162
	v_lshl_add_u32 v123, v125, 4, v123
	v_bfe_u32 v125, v0, 2, 2
	v_lshl_add_u32 v123, v125, 5, v123
	s_cmp_lt_u32 s43, 3
	s_cbranch_scc1 .Latt_nok2
	s_add_i32 s46, s31, 0x10000
	s_mov_b32 m0, s46
	v_lshl_add_u64 v[162:163], v[140:141], 0, s[18:19]
	global_load_lds_dwordx4 v[140:141], off
	s_add_i32 m0, s46, 0x2000
	s_nop 0
	global_load_lds_dwordx4 v[162:163], off
	v_lshl_add_u64 v[140:141], v[140:141], 0, s[20:21]

; #define ATT_LAS __attribute__((address_space(3)))
; __device__ __forceinline__ int crow(int r, int hi) { return (r & 3) + 8 * (r >> 2) + 4 * hi; }
; __device__ __forceinline__ unsigned cvtpk_s(float lo, float hi) { f32x2_t v = {lo, hi}; bf16x2_t b = __builtin_convertvector(v, bf16x2_t); return __builtin_bit_cast(unsigned, b); }
; __device__ __forceinline__ void attn_unit(const int b, const int h, const int qb, const bf16_t* Q, const bf16_t* K, const bf16_t* V, bf16_t* O, ATT_LAS char* shm, const float lam) {
;     ...
;     asm volatile("s_waitcnt lgkmcnt(0)\n\ts_barrier" ::: "memory");
;     if (sub == 1) {
;         ATT_LAS bf16_t* stg = (ATT_LAS bf16_t*)(shm + 65536 + w4 * 8192);
; #pragma unroll
;         for (int r = 0; r < 16; ++r) { const int rw = crow(r, hi); const float rli = __shfl(rl, rw) * lam;
;             float v[4]; float ss = 0.f;
; #pragma unroll
;             for (int d0 = 0; d0 < 4; ++d0) { v[d0] = xa[(d0 * 16 + r) * 64] - o[d0][r] * rli; ss += v[d0] * v[d0]; }
;             ss += __shfl_xor(ss, 1); ss += __shfl_xor(ss, 2); ss += __shfl_xor(ss, 4); ss += __shfl_xor(ss, 8); ss += __shfl_xor(ss, 16);
;             const float rn = __builtin_amdgcn_rsqf(ss * (1.0f / 128.0f) + 1e-6f);
; #pragma unroll
;             for (int d0 = 0; d0 < 4; ++d0) stg[rw * 128 + d0 * 32 + r32] = (bf16_t)(cvtpk_s(v[d0] * rn, 0.f) & 0xffffu); }
.LBB0_476:
	s_waitcnt lgkmcnt(0)
	s_barrier
	s_cmp_lg_u32 s39, 1
	s_cbranch_scc1 .LBB0_465
	ds_bpermute_b32 v70, v174, v0
	ds_read2st64_b32 v[66:67], v80 offset1:1
	ds_read2st64_b32 v[68:69], v80 offset0:16 offset1:17
	s_add_i32 s3, s38, 0
	s_add_i32 s3, s3, 0x10000
	s_add_u32 s16, s54, s26
	s_waitcnt lgkmcnt(2)
	v_mul_f32_e32 v81, v149, v70
	ds_read2st64_b32 v[70:71], v80 offset0:2 offset1:3
	ds_read2st64_b32 v[76:77], v80 offset0:4 offset1:5
	ds_read2st64_b32 v[72:73], v80 offset0:6 offset1:7
	ds_read2st64_b32 v[82:83], v80 offset0:18 offset1:19
	ds_read2st64_b32 v[84:85], v80 offset0:20 offset1:21
	ds_read2st64_b32 v[74:75], v80 offset0:22 offset1:23
	ds_read2st64_b32 v[86:87], v80 offset0:32 offset1:33
	ds_read2st64_b32 v[88:89], v80 offset0:34 offset1:35
	ds_read2st64_b32 v[90:91], v80 offset0:36 offset1:37
	ds_read2st64_b32 v[78:79], v80 offset0:38 offset1:39
	ds_read2st64_b32 v[92:93], v80 offset0:48 offset1:49
	s_waitcnt lgkmcnt(12)
	v_fma_f32 v50, -v50, v81, v66
	s_waitcnt lgkmcnt(11)
	v_fma_f32 v66, -v34, v81, v68
	v_mul_f32_e32 v34, v66, v66
	v_fmac_f32_e32 v34, v50, v50
	s_waitcnt lgkmcnt(4)
	v_fma_f32 v18, -v18, v81, v86
	v_fmac_f32_e32 v34, v18, v18
	s_waitcnt lgkmcnt(0)
	v_fma_f32 v2, -v2, v81, v92
	v_fmac_f32_e32 v34, v2, v2
	ds_bpermute_b32 v68, v144, v34
	ds_bpermute_b32 v81, v175, v0
	ds_read2st64_b32 v[94:95], v80 offset0:50 offset1:51
	ds_read2st64_b32 v[96:97], v80 offset0:52 offset1:53
	ds_read2st64_b32 v[98:99], v80 offset0:54 offset1:55
	s_addc_u32 s27, s55, s27
	s_lshl_b32 s26, s35, 1
	s_waitcnt lgkmcnt(4)
	v_add_f32_e32 v34, v34, v68
	ds_bpermute_b32 v68, v145, v34
	s_waitcnt lgkmcnt(4)
	v_mul_f32_e32 v81, v149, v81
	v_fma_f32 v35, -v35, v81, v69
	v_fma_f32 v51, -v51, v81, v67
	v_mul_f32_e32 v67, v35, v35
	s_waitcnt lgkmcnt(0)
	v_add_f32_e32 v34, v34, v68
	ds_bpermute_b32 v68, v146, v34
	v_fmac_f32_e32 v67, v51, v51
	v_fma_f32 v19, -v19, v81, v87
	v_fmac_f32_e32 v67, v19, v19
	v_fma_f32 v3, -v3, v81, v93
	s_waitcnt lgkmcnt(0)
	v_add_f32_e32 v34, v34, v68
	ds_bpermute_b32 v68, v147, v34
	v_fmac_f32_e32 v67, v3, v3
	ds_bpermute_b32 v69, v144, v67
	s_add_u32 s26, s16, s26
	s_addc_u32 s27, s27, 0
	s_waitcnt lgkmcnt(1)
	v_add_f32_e32 v68, v34, v68
	ds_bpermute_b32 v86, v148, v68
	v_lshl_add_u32 v34, v151, 1, s3
	v_add_u32_e32 v81, v34, v153
	v_mov_b32_e32 v123, v1
	v_mov_b32_e32 v125, v1
	s_waitcnt lgkmcnt(0)
	v_add_f32_e32 v68, v68, v86
	v_fmamk_f32 v68, v68, 0x3c000000, v214
	v_rsq_f32_e32 v68, v68
	v_mov_b32_e32 v127, v1
	v_mov_b32_e32 v129, v1
	v_mov_b32_e32 v131, v1
	v_mul_f32_e32 v50, v50, v68
	v_cvt_pk_bf16_f32 v50, v50, s0
	ds_write_b16 v81, v50
	v_add_f32_e32 v50, v67, v69
	ds_bpermute_b32 v67, v145, v50
	v_mul_f32_e32 v66, v66, v68
	v_cvt_pk_bf16_f32 v66, v66, s0
	ds_write_b16 v81, v66 offset:64
	v_mul_f32_e32 v18, v18, v68
	s_waitcnt lgkmcnt(1)
	v_add_f32_e32 v50, v50, v67
	ds_bpermute_b32 v66, v146, v50
	ds_bpermute_b32 v67, v177, v0
	v_cvt_pk_bf16_f32 v18, v18, s0
	ds_write_b16 v81, v18 offset:128
	v_mul_f32_e32 v2, v2, v68
	s_waitcnt lgkmcnt(2)
	v_add_f32_e32 v18, v50, v66
	s_waitcnt lgkmcnt(1)
	v_mul_f32_e32 v66, v149, v67
	v_fma_f32 v36, -v36, v66, v82
	v_fma_f32 v52, -v52, v66, v70
	v_mul_f32_e32 v67, v36, v36
	v_fmac_f32_e32 v67, v52, v52
	v_fma_f32 v20, -v20, v66, v88
	v_fmac_f32_e32 v67, v20, v20
	v_fma_f32 v4, -v4, v66, v94
	ds_bpermute_b32 v50, v147, v18
	v_fmac_f32_e32 v67, v4, v4
	ds_bpermute_b32 v66, v144, v67
	v_cvt_pk_bf16_f32 v2, v2, s0
	ds_write_b16 v81, v2 offset:192
	s_waitcnt lgkmcnt(2)
	v_add_f32_e32 v18, v18, v50
	ds_bpermute_b32 v50, v148, v18
	s_waitcnt lgkmcnt(2)
	v_add_f32_e32 v2, v67, v66
	ds_bpermute_b32 v66, v145, v2
	v_mov_b32_e32 v133, v1
	v_mov_b32_e32 v135, v1
	s_waitcnt lgkmcnt(1)
	v_add_f32_e32 v18, v18, v50
	v_fmamk_f32 v18, v18, 0x3c000000, v214
	s_waitcnt lgkmcnt(0)
	v_add_f32_e32 v2, v2, v66
	v_rsq_f32_e32 v18, v18
	ds_bpermute_b32 v66, v146, v2
	v_add_u32_e32 v50, v34, v176
	v_mov_b32_e32 v137, v1
	v_mul_f32_e32 v51, v51, v18
	v_cvt_pk_bf16_f32 v51, v51, s0
	s_waitcnt lgkmcnt(0)
	v_add_f32_e32 v2, v2, v66
	ds_write_b16 v50, v51
	ds_bpermute_b32 v51, v147, v2
	v_mul_f32_e32 v35, v35, v18
	v_cvt_pk_bf16_f32 v35, v35, s0
	v_mul_f32_e32 v19, v19, v18
	v_mul_f32_e32 v3, v3, v18
	s_waitcnt lgkmcnt(0)
	v_add_f32_e32 v2, v2, v51
	ds_bpermute_b32 v18, v179, v0
	ds_write_b16 v50, v35 offset:64
	ds_bpermute_b32 v35, v148, v2
	v_cvt_pk_bf16_f32 v19, v19, s0
	ds_write_b16 v50, v19 offset:128
	s_waitcnt lgkmcnt(3)
	v_mul_f32_e32 v18, v149, v18
	v_fma_f32 v19, -v53, v18, v71
	s_waitcnt lgkmcnt(1)
	v_add_f32_e32 v2, v2, v35
	v_fma_f32 v35, -v37, v18, v83
	v_mul_f32_e32 v37, v35, v35
	v_fmac_f32_e32 v37, v19, v19
	v_fma_f32 v21, -v21, v18, v89
	v_fmac_f32_e32 v37, v21, v21
	v_fma_f32 v5, -v5, v18, v95
	v_fmac_f32_e32 v37, v5, v5
	ds_bpermute_b32 v18, v144, v37
	v_fmamk_f32 v2, v2, 0x3c000000, v214
	v_rsq_f32_e32 v2, v2
	v_cvt_pk_bf16_f32 v3, v3, s0
	ds_write_b16 v50, v3 offset:192
	s_waitcnt lgkmcnt(1)
	v_add_f32_e32 v18, v37, v18
	ds_bpermute_b32 v37, v145, v18
	v_mul_f32_e32 v36, v36, v2
	v_add_u32_e32 v3, v34, v178
	v_cvt_pk_bf16_f32 v36, v36, s0
	ds_write_b16 v3, v36 offset:64
	s_waitcnt lgkmcnt(1)
	v_add_f32_e32 v18, v18, v37
	ds_bpermute_b32 v36, v146, v18
	ds_bpermute_b32 v37, v181, v0
	v_mul_f32_e32 v50, v52, v2
	v_cvt_pk_bf16_f32 v50, v50, s0
	ds_write_b16 v3, v50
	s_waitcnt lgkmcnt(2)
	v_add_f32_e32 v18, v18, v36
	s_waitcnt lgkmcnt(1)
; __device__ __forceinline__ int crow(int r, int hi) { return (r & 3) + 8 * (r >> 2) + 4 * hi; }
; __device__ __forceinline__ unsigned cvtpk_s(float lo, float hi) { f32x2_t v = {lo, hi}; bf16x2_t b = __builtin_convertvector(v, bf16x2_t); return __builtin_bit_cast(unsigned, b); }
; __device__ __forceinline__ void attn_unit(const int b, const int h, const int qb, const bf16_t* Q, const bf16_t* K, const bf16_t* V, bf16_t* O, ATT_LAS char* shm, const float lam) {
;     ...
;         for (int r = 0; r < 16; ++r) { const int rw = crow(r, hi); const float rli = __shfl(rl, rw) * lam;
;             float v[4]; float ss = 0.f;
; #pragma unroll
;             for (int d0 = 0; d0 < 4; ++d0) { v[d0] = xa[(d0 * 16 + r) * 64] - o[d0][r] * rli; ss += v[d0] * v[d0]; }
;             ss += __shfl_xor(ss, 1); ss += __shfl_xor(ss, 2); ss += __shfl_xor(ss, 4); ss += __shfl_xor(ss, 8); ss += __shfl_xor(ss, 16);
;             const float rn = __builtin_amdgcn_rsqf(ss * (1.0f / 128.0f) + 1e-6f);
; #pragma unroll
;             for (int d0 = 0; d0 < 4; ++d0) stg[rw * 128 + d0 * 32 + r32] = (bf16_t)(cvtpk_s(v[d0] * rn, 0.f) & 0xffffu); }
	v_mul_f32_e32 v36, v149, v37
	v_fma_f32 v38, -v38, v36, v84
	v_fma_f32 v37, -v54, v36, v76
	v_mul_f32_e32 v50, v38, v38
	v_fmac_f32_e32 v50, v37, v37
	v_fma_f32 v22, -v22, v36, v90
	v_mul_f32_e32 v20, v20, v2
	v_fmac_f32_e32 v50, v22, v22
	v_fma_f32 v6, -v6, v36, v96
	v_cvt_pk_bf16_f32 v20, v20, s0
	v_fmac_f32_e32 v50, v6, v6
	ds_write_b16 v3, v20 offset:128
	ds_bpermute_b32 v20, v147, v18
	ds_bpermute_b32 v36, v144, v50
	v_mul_f32_e32 v2, v4, v2
	v_cvt_pk_bf16_f32 v2, v2, s0
	ds_write_b16 v3, v2 offset:192
	s_waitcnt lgkmcnt(2)
	v_add_f32_e32 v4, v18, v20
	s_waitcnt lgkmcnt(1)
	v_add_f32_e32 v20, v50, v36
	ds_bpermute_b32 v36, v145, v20
	ds_bpermute_b32 v18, v148, v4
	v_add_u32_e32 v71, v34, v186
	v_mov_b32_e32 v139, v1
	s_waitcnt lgkmcnt(1)
	v_add_f32_e32 v3, v20, v36
	s_waitcnt lgkmcnt(0)
	v_add_f32_e32 v2, v4, v18
	ds_bpermute_b32 v4, v146, v3
	v_fmamk_f32 v2, v2, 0x3c000000, v214
	v_rsq_f32_e32 v2, v2
	v_add_u32_e32 v18, v34, v180
	s_waitcnt lgkmcnt(0)
	v_add_f32_e32 v3, v3, v4
	v_mul_f32_e32 v19, v19, v2
	ds_bpermute_b32 v4, v147, v3
	v_cvt_pk_bf16_f32 v19, v19, s0
	ds_write_b16 v18, v19
	v_mul_f32_e32 v19, v35, v2
	v_cvt_pk_bf16_f32 v19, v19, s0
	ds_write_b16 v18, v19 offset:64
	v_mul_f32_e32 v19, v21, v2
	s_waitcnt lgkmcnt(2)
	v_add_f32_e32 v3, v3, v4
	v_cvt_pk_bf16_f32 v19, v19, s0
	ds_bpermute_b32 v4, v148, v3
	ds_write_b16 v18, v19 offset:128
	ds_bpermute_b32 v19, v183, v0
	v_mul_f32_e32 v2, v5, v2
	v_cvt_pk_bf16_f32 v2, v2, s0
	s_waitcnt lgkmcnt(2)
	v_add_f32_e32 v3, v3, v4
	v_fmamk_f32 v3, v3, 0x3c000000, v214
	s_waitcnt lgkmcnt(0)
	v_mul_f32_e32 v4, v149, v19
	v_fma_f32 v19, -v39, v4, v85
	v_fma_f32 v5, -v55, v4, v77
	v_mul_f32_e32 v20, v19, v19
	v_fmac_f32_e32 v20, v5, v5
	v_fma_f32 v21, -v23, v4, v91
	v_fmac_f32_e32 v20, v21, v21
	v_fma_f32 v4, -v7, v4, v97
	v_fmac_f32_e32 v20, v4, v4
	ds_bpermute_b32 v7, v144, v20
	v_rsq_f32_e32 v3, v3
	ds_write_b16 v18, v2 offset:192
	v_add_u32_e32 v2, v34, v182
	s_waitcnt lgkmcnt(1)
	v_add_f32_e32 v7, v20, v7
	ds_bpermute_b32 v20, v145, v7
	v_mul_f32_e32 v18, v37, v3
	v_cvt_pk_bf16_f32 v18, v18, s0
	ds_write_b16 v2, v18
	v_mul_f32_e32 v18, v38, v3
	s_waitcnt lgkmcnt(1)
	v_add_f32_e32 v7, v7, v20
	ds_bpermute_b32 v20, v146, v7
	v_cvt_pk_bf16_f32 v18, v18, s0
	ds_write_b16 v2, v18 offset:64
	v_mul_f32_e32 v18, v22, v3
	v_cvt_pk_bf16_f32 v18, v18, s0
	s_waitcnt lgkmcnt(1)
	v_add_f32_e32 v7, v7, v20
	v_mul_f32_e32 v3, v6, v3
	ds_bpermute_b32 v6, v185, v0
	ds_write_b16 v2, v18 offset:128
	ds_bpermute_b32 v18, v147, v7
	v_cvt_pk_bf16_f32 v3, v3, s0
	ds_write_b16 v2, v3 offset:192
	s_waitcnt lgkmcnt(3)
	v_mul_f32_e32 v6, v149, v6
	v_fma_f32 v22, -v24, v6, v78
	s_waitcnt lgkmcnt(1)
	v_add_f32_e32 v2, v7, v18
	v_fma_f32 v18, -v40, v6, v74
	v_fma_f32 v7, -v56, v6, v72
	v_mul_f32_e32 v20, v18, v18
	v_fmac_f32_e32 v20, v7, v7
	v_fmac_f32_e32 v20, v22, v22
	v_fma_f32 v6, -v8, v6, v98
	ds_bpermute_b32 v3, v148, v2
	v_fmac_f32_e32 v20, v6, v6
	ds_bpermute_b32 v8, v144, v20
	s_waitcnt lgkmcnt(1)
	v_add_f32_e32 v2, v2, v3
	v_fmamk_f32 v2, v2, 0x3c000000, v214
	s_waitcnt lgkmcnt(0)
	v_add_f32_e32 v8, v20, v8
	v_rsq_f32_e32 v2, v2
	ds_bpermute_b32 v20, v145, v8
	v_add_u32_e32 v3, v34, v184
	v_mul_f32_e32 v5, v5, v2
	v_cvt_pk_bf16_f32 v5, v5, s0
	s_waitcnt lgkmcnt(0)
	v_add_f32_e32 v8, v8, v20
	ds_write_b16 v3, v5
	v_mul_f32_e32 v5, v19, v2
	ds_bpermute_b32 v19, v146, v8
	v_cvt_pk_bf16_f32 v5, v5, s0
	ds_write_b16 v3, v5 offset:64
	v_mul_f32_e32 v5, v21, v2
	v_cvt_pk_bf16_f32 v5, v5, s0
	ds_write_b16 v3, v5 offset:128
	ds_bpermute_b32 v5, v187, v0
	s_waitcnt lgkmcnt(3)
	v_add_f32_e32 v8, v8, v19
	ds_bpermute_b32 v19, v147, v8
	v_mul_f32_e32 v2, v4, v2
	v_cvt_pk_bf16_f32 v2, v2, s0
	s_waitcnt lgkmcnt(1)
	v_mul_f32_e32 v5, v149, v5
	v_fma_f32 v68, -v41, v5, v75
	s_waitcnt lgkmcnt(0)
	v_add_f32_e32 v4, v8, v19
	v_fma_f32 v35, -v57, v5, v73
	v_mul_f32_e32 v19, v68, v68
	v_fmac_f32_e32 v19, v35, v35
	v_fma_f32 v69, -v25, v5, v79
	v_fmac_f32_e32 v19, v69, v69
	v_fma_f32 v70, -v9, v5, v99
	v_fmac_f32_e32 v19, v70, v70
	ds_bpermute_b32 v5, v144, v19
	ds_bpermute_b32 v8, v148, v4
	ds_write_b16 v3, v2 offset:192
	s_waitcnt lgkmcnt(2)
	v_add_f32_e32 v3, v19, v5
	s_waitcnt lgkmcnt(1)
	v_add_f32_e32 v2, v4, v8
	ds_bpermute_b32 v4, v145, v3
	v_fmamk_f32 v2, v2, 0x3c000000, v214
	v_rsq_f32_e32 v2, v2
	s_waitcnt lgkmcnt(0)
	v_add_f32_e32 v3, v3, v4
	ds_bpermute_b32 v4, v146, v3
	v_mul_f32_e32 v5, v7, v2
	v_cvt_pk_bf16_f32 v5, v5, s0
	ds_write_b16 v71, v5
	v_mul_f32_e32 v5, v18, v2
	s_waitcnt lgkmcnt(1)
	v_add_f32_e32 v3, v3, v4
	ds_bpermute_b32 v4, v147, v3
	ds_bpermute_b32 v7, v189, v0
	v_cvt_pk_bf16_f32 v5, v5, s0
	ds_write_b16 v71, v5 offset:64
	v_mul_f32_e32 v5, v22, v2
	v_cvt_pk_bf16_f32 v5, v5, s0
	ds_write_b16 v71, v5 offset:128
	v_mul_f32_e32 v72, v6, v2
	s_waitcnt lgkmcnt(3)
	v_add_f32_e32 v73, v3, v4
	s_waitcnt lgkmcnt(2)
	v_mul_f32_e32 v75, v149, v7
	ds_read2st64_b32 v[2:3], v80 offset0:8 offset1:9
	ds_read2st64_b32 v[4:5], v80 offset0:24 offset1:25
	ds_read2st64_b32 v[6:7], v80 offset0:10 offset1:11
	ds_read2st64_b32 v[20:21], v80 offset0:12 offset1:13
	ds_read2st64_b32 v[8:9], v80 offset0:14 offset1:15
	ds_read2st64_b32 v[36:37], v80 offset0:26 offset1:27
	ds_read2st64_b32 v[38:39], v80 offset0:28 offset1:29
	ds_read2st64_b32 v[18:19], v80 offset0:30 offset1:31
	ds_read2st64_b32 v[40:41], v80 offset0:40 offset1:41
	ds_read2st64_b32 v[50:51], v80 offset0:42 offset1:43
	ds_read2st64_b32 v[52:53], v80 offset0:44 offset1:45
	ds_read2st64_b32 v[22:23], v80 offset0:46 offset1:47
	ds_read2st64_b32 v[54:55], v80 offset0:56 offset1:57
	s_waitcnt lgkmcnt(11)
; __device__ __forceinline__ int crow(int r, int hi) { return (r & 3) + 8 * (r >> 2) + 4 * hi; }
; __device__ __forceinline__ unsigned cvtpk_s(float lo, float hi) { f32x2_t v = {lo, hi}; bf16x2_t b = __builtin_convertvector(v, bf16x2_t); return __builtin_bit_cast(unsigned, b); }
; __device__ __forceinline__ void attn_unit(const int b, const int h, const int qb, const bf16_t* Q, const bf16_t* K, const bf16_t* V, bf16_t* O, ATT_LAS char* shm, const float lam) {
;     ...
;         for (int r = 0; r < 16; ++r) { const int rw = crow(r, hi); const float rli = __shfl(rl, rw) * lam;
;             float v[4]; float ss = 0.f;
; #pragma unroll
;             for (int d0 = 0; d0 < 4; ++d0) { v[d0] = xa[(d0 * 16 + r) * 64] - o[d0][r] * rli; ss += v[d0] * v[d0]; }
;             ss += __shfl_xor(ss, 1); ss += __shfl_xor(ss, 2); ss += __shfl_xor(ss, 4); ss += __shfl_xor(ss, 8); ss += __shfl_xor(ss, 16);
;             const float rn = __builtin_amdgcn_rsqf(ss * (1.0f / 128.0f) + 1e-6f);
; #pragma unroll
;             for (int d0 = 0; d0 < 4; ++d0) stg[rw * 128 + d0 * 32 + r32] = (bf16_t)(cvtpk_s(v[d0] * rn, 0.f) & 0xffffu); }
	v_fma_f32 v4, -v42, v75, v4
	v_fma_f32 v2, -v58, v75, v2
	v_mul_f32_e32 v42, v4, v4
	v_fmac_f32_e32 v42, v2, v2
	s_waitcnt lgkmcnt(4)
	v_fma_f32 v26, -v26, v75, v40
	v_fmac_f32_e32 v42, v26, v26
	s_waitcnt lgkmcnt(0)
	v_fma_f32 v10, -v10, v75, v54
	v_fmac_f32_e32 v42, v10, v10
	ds_bpermute_b32 v40, v144, v42
	ds_bpermute_b32 v74, v148, v73
	v_cvt_pk_bf16_f32 v54, v72, s0
	ds_read2st64_b32 v[56:57], v80 offset0:58 offset1:59
	ds_read2st64_b32 v[66:67], v80 offset0:60 offset1:61
	ds_read2st64_b32 v[24:25], v80 offset0:62 offset1:63
	ds_write_b16 v71, v54 offset:192
	s_waitcnt lgkmcnt(5)
	v_add_f32_e32 v40, v42, v40
	s_waitcnt lgkmcnt(4)
	v_add_f32_e32 v58, v73, v74
	ds_bpermute_b32 v42, v145, v40
	v_fmamk_f32 v58, v58, 0x3c000000, v214
	v_rsq_f32_e32 v58, v58
	v_add_u32_e32 v54, v34, v188
	s_waitcnt lgkmcnt(0)
	v_add_f32_e32 v40, v40, v42
	v_mul_f32_e32 v35, v35, v58
	ds_bpermute_b32 v42, v146, v40
	v_cvt_pk_bf16_f32 v35, v35, s0
	ds_write_b16 v54, v35
	v_mul_f32_e32 v35, v68, v58
	ds_bpermute_b32 v68, v191, v0
	v_cvt_pk_bf16_f32 v35, v35, s0
	ds_write_b16 v54, v35 offset:64
	s_waitcnt lgkmcnt(3)
	v_add_f32_e32 v35, v40, v42
	v_mul_f32_e32 v42, v69, v58
	v_cvt_pk_bf16_f32 v42, v42, s0
	ds_bpermute_b32 v40, v147, v35
	ds_write_b16 v54, v42 offset:128
	s_waitcnt lgkmcnt(3)
	v_mul_f32_e32 v42, v149, v68
	v_fma_f32 v5, -v43, v42, v5
	v_fma_f32 v3, -v59, v42, v3
	v_mul_f32_e32 v43, v5, v5
	v_fmac_f32_e32 v43, v3, v3
	v_fma_f32 v27, -v27, v42, v41
	v_fmac_f32_e32 v43, v27, v27
	v_fma_f32 v11, -v11, v42, v55
	s_waitcnt lgkmcnt(1)
	v_add_f32_e32 v35, v35, v40
	v_fmac_f32_e32 v43, v11, v11
	ds_bpermute_b32 v40, v148, v35
	ds_bpermute_b32 v41, v144, v43
	v_mul_f32_e32 v42, v70, v58
	v_cvt_pk_bf16_f32 v42, v42, s0
	ds_write_b16 v54, v42 offset:192
	s_waitcnt lgkmcnt(2)
	v_add_f32_e32 v35, v35, v40
	s_waitcnt lgkmcnt(1)
	v_add_f32_e32 v40, v43, v41
	ds_bpermute_b32 v41, v145, v40
	v_fmamk_f32 v35, v35, 0x3c000000, v214
	v_rsq_f32_e32 v35, v35
	v_add_u32_e32 v42, v34, v190
	s_waitcnt lgkmcnt(0)
	v_add_f32_e32 v40, v40, v41
	ds_bpermute_b32 v41, v146, v40
	v_mul_f32_e32 v2, v2, v35
	v_cvt_pk_bf16_f32 v2, v2, s0
	ds_write_b16 v42, v2
	v_mul_f32_e32 v2, v4, v35
	s_waitcnt lgkmcnt(1)
	v_add_f32_e32 v4, v40, v41
	ds_bpermute_b32 v40, v147, v4
	v_cvt_pk_bf16_f32 v2, v2, s0
	ds_write_b16 v42, v2 offset:64
	v_mul_f32_e32 v2, v26, v35
	v_cvt_pk_bf16_f32 v2, v2, s0
	ds_write_b16 v42, v2 offset:128
	s_waitcnt lgkmcnt(2)
	v_add_f32_e32 v2, v4, v40
	ds_bpermute_b32 v4, v148, v2
	ds_bpermute_b32 v26, v193, v0
	v_mul_f32_e32 v10, v10, v35
	v_cvt_pk_bf16_f32 v10, v10, s0
	ds_write_b16 v42, v10 offset:192
	s_waitcnt lgkmcnt(2)
	v_add_f32_e32 v2, v2, v4
	s_waitcnt lgkmcnt(1)
	v_mul_f32_e32 v4, v149, v26
	v_fma_f32 v10, -v44, v4, v36
	v_fma_f32 v6, -v60, v4, v6
	v_mul_f32_e32 v26, v10, v10
	v_fmac_f32_e32 v26, v6, v6
	v_fma_f32 v28, -v28, v4, v50
	v_fmamk_f32 v2, v2, 0x3c000000, v214
	v_fmac_f32_e32 v26, v28, v28
	v_fma_f32 v4, -v12, v4, v56
	v_rsq_f32_e32 v2, v2
	v_fmac_f32_e32 v26, v4, v4
	ds_bpermute_b32 v12, v144, v26
	v_add_u32_e32 v35, v34, v192
	v_mul_f32_e32 v3, v3, v2
	v_cvt_pk_bf16_f32 v3, v3, s0
	ds_write_b16 v35, v3
	s_waitcnt lgkmcnt(1)
	v_add_f32_e32 v3, v26, v12
	ds_bpermute_b32 v12, v145, v3
	ds_bpermute_b32 v26, v195, v0
	v_mul_f32_e32 v5, v5, v2
	v_cvt_pk_bf16_f32 v5, v5, s0
	ds_write_b16 v35, v5 offset:64
	s_waitcnt lgkmcnt(2)
	v_add_f32_e32 v3, v3, v12
	ds_bpermute_b32 v12, v146, v3
	v_mul_f32_e32 v5, v27, v2
	v_mul_f32_e32 v2, v11, v2
	s_waitcnt lgkmcnt(2)
	v_mul_f32_e32 v11, v149, v26
	v_fma_f32 v7, -v61, v11, v7
	s_waitcnt lgkmcnt(0)
	v_add_f32_e32 v3, v3, v12
	v_fma_f32 v12, -v45, v11, v37
	v_mul_f32_e32 v26, v12, v12
	v_fmac_f32_e32 v26, v7, v7
	v_fma_f32 v27, -v29, v11, v51
	v_cvt_pk_bf16_f32 v5, v5, s0
	v_fmac_f32_e32 v26, v27, v27
	v_fma_f32 v11, -v13, v11, v57
	ds_write_b16 v35, v5 offset:128
	ds_bpermute_b32 v5, v147, v3
	v_fmac_f32_e32 v26, v11, v11
	ds_bpermute_b32 v13, v144, v26
	v_cvt_pk_bf16_f32 v2, v2, s0
	ds_write_b16 v35, v2 offset:192
	s_waitcnt lgkmcnt(2)
	v_add_f32_e32 v3, v3, v5
	ds_bpermute_b32 v5, v148, v3
	s_waitcnt lgkmcnt(2)
	v_add_f32_e32 v2, v26, v13
	ds_bpermute_b32 v13, v145, v2
	s_waitcnt lgkmcnt(1)
	v_add_f32_e32 v3, v3, v5
	v_fmamk_f32 v3, v3, 0x3c000000, v214
	s_waitcnt lgkmcnt(0)
	v_add_f32_e32 v2, v2, v13
	v_rsq_f32_e32 v3, v3
	ds_bpermute_b32 v13, v146, v2
	v_add_u32_e32 v5, v34, v194
	v_mul_f32_e32 v6, v6, v3
	v_cvt_pk_bf16_f32 v6, v6, s0
	s_waitcnt lgkmcnt(0)
	v_add_f32_e32 v2, v2, v13
	ds_write_b16 v5, v6
	v_mul_f32_e32 v6, v10, v3
	ds_bpermute_b32 v10, v147, v2
	v_cvt_pk_bf16_f32 v6, v6, s0
	ds_write_b16 v5, v6 offset:64
	v_mul_f32_e32 v6, v28, v3
	v_mul_f32_e32 v3, v4, v3
	s_waitcnt lgkmcnt(1)
	v_add_f32_e32 v2, v2, v10
	ds_bpermute_b32 v4, v197, v0
	ds_bpermute_b32 v10, v148, v2
	v_cvt_pk_bf16_f32 v6, v6, s0
	ds_write_b16 v5, v6 offset:128
	v_cvt_pk_bf16_f32 v3, v3, s0
	s_waitcnt lgkmcnt(2)
	v_mul_f32_e32 v4, v149, v4
	s_waitcnt lgkmcnt(1)
	v_add_f32_e32 v2, v2, v10
	v_fma_f32 v10, -v46, v4, v38
	v_fma_f32 v6, -v62, v4, v20
	v_mul_f32_e32 v13, v10, v10
	v_fmac_f32_e32 v13, v6, v6
	v_fma_f32 v20, -v30, v4, v52
	v_fmac_f32_e32 v13, v20, v20
	v_fma_f32 v4, -v14, v4, v66
	v_fmac_f32_e32 v13, v4, v4
	v_fmamk_f32 v2, v2, 0x3c000000, v214
	ds_bpermute_b32 v14, v144, v13
	v_rsq_f32_e32 v2, v2
	ds_write_b16 v5, v3 offset:192
	v_add_u32_e32 v3, v34, v196
	v_mul_f32_e32 v5, v7, v2
	s_waitcnt lgkmcnt(1)
	v_add_f32_e32 v7, v13, v14
	ds_bpermute_b32 v13, v145, v7
	v_cvt_pk_bf16_f32 v5, v5, s0
	ds_write_b16 v3, v5
	v_mul_f32_e32 v5, v12, v2
	v_cvt_pk_bf16_f32 v5, v5, s0
	ds_write_b16 v3, v5 offset:64
	s_waitcnt lgkmcnt(2)
; #define ATT_LAS __attribute__((address_space(3)))
; __device__ __forceinline__ int crow(int r, int hi) { return (r & 3) + 8 * (r >> 2) + 4 * hi; }
; __device__ __forceinline__ unsigned cvtpk_s(float lo, float hi) { f32x2_t v = {lo, hi}; bf16x2_t b = __builtin_convertvector(v, bf16x2_t); return __builtin_bit_cast(unsigned, b); }
; __device__ __forceinline__ void attn_unit(const int b, const int h, const int qb, const bf16_t* Q, const bf16_t* K, const bf16_t* V, bf16_t* O, ATT_LAS char* shm, const float lam) {
;     ...
;         for (int r = 0; r < 16; ++r) { const int rw = crow(r, hi); const float rli = __shfl(rl, rw) * lam;
;             float v[4]; float ss = 0.f;
; #pragma unroll
;             for (int d0 = 0; d0 < 4; ++d0) { v[d0] = xa[(d0 * 16 + r) * 64] - o[d0][r] * rli; ss += v[d0] * v[d0]; }
;             ss += __shfl_xor(ss, 1); ss += __shfl_xor(ss, 2); ss += __shfl_xor(ss, 4); ss += __shfl_xor(ss, 8); ss += __shfl_xor(ss, 16);
;             const float rn = __builtin_amdgcn_rsqf(ss * (1.0f / 128.0f) + 1e-6f);
; #pragma unroll
;             for (int d0 = 0; d0 < 4; ++d0) stg[rw * 128 + d0 * 32 + r32] = (bf16_t)(cvtpk_s(v[d0] * rn, 0.f) & 0xffffu); }
;         asm volatile("s_waitcnt lgkmcnt(0)" ::: "memory");
;         bf16_t* obase = O + (rowbase + q0 + w4 * QBLK) * PITCH + h * 128;
; #pragma unroll
;         for (int i = 0; i < 8; ++i) { const int row = i * 4 + (lane >> 4), ch = lane & 15; const u32x4 w = *(const ATT_LAS u32x4*)(stg + row * 128 + ch * 8); *(u32x4*)(obase + (long)row * PITCH + ch * 8) = w; }
	v_add_f32_e32 v5, v7, v13
	ds_bpermute_b32 v13, v199, v0
	v_mul_f32_e32 v12, v27, v2
	ds_bpermute_b32 v7, v146, v5
	v_cvt_pk_bf16_f32 v12, v12, s0
	ds_write_b16 v3, v12 offset:128
	s_waitcnt lgkmcnt(2)
	v_mul_f32_e32 v12, v149, v13
	v_fma_f32 v14, -v47, v12, v39
	v_fma_f32 v13, -v63, v12, v21
	v_mul_f32_e32 v21, v14, v14
	v_fmac_f32_e32 v21, v13, v13
	v_fma_f32 v26, -v31, v12, v53
	s_waitcnt lgkmcnt(1)
	v_add_f32_e32 v5, v5, v7
	v_fmac_f32_e32 v21, v26, v26
	v_fma_f32 v12, -v15, v12, v67
	ds_bpermute_b32 v7, v147, v5
	v_fmac_f32_e32 v21, v12, v12
	ds_bpermute_b32 v15, v144, v21
	v_mul_f32_e32 v2, v11, v2
	v_cvt_pk_bf16_f32 v2, v2, s0
	s_waitcnt lgkmcnt(1)
	v_add_f32_e32 v5, v5, v7
	ds_bpermute_b32 v7, v148, v5
	s_waitcnt lgkmcnt(1)
	v_add_f32_e32 v11, v21, v15
	ds_bpermute_b32 v15, v145, v11
	ds_write_b16 v3, v2 offset:192
	s_waitcnt lgkmcnt(2)
	v_add_f32_e32 v2, v5, v7
	v_fmamk_f32 v2, v2, 0x3c000000, v214
	s_waitcnt lgkmcnt(1)
	v_add_f32_e32 v3, v11, v15
	v_rsq_f32_e32 v2, v2
	ds_bpermute_b32 v5, v146, v3
	v_add_u32_e32 v7, v34, v198
	v_mul_f32_e32 v6, v6, v2
	v_cvt_pk_bf16_f32 v6, v6, s0
	s_waitcnt lgkmcnt(0)
	v_add_f32_e32 v3, v3, v5
	ds_write_b16 v7, v6
	ds_bpermute_b32 v5, v147, v3
	v_mul_f32_e32 v6, v10, v2
	v_cvt_pk_bf16_f32 v6, v6, s0
	ds_write_b16 v7, v6 offset:64
	v_mul_f32_e32 v6, v20, v2
	v_cvt_pk_bf16_f32 v6, v6, s0
	ds_write_b16 v7, v6 offset:128
	ds_bpermute_b32 v6, v201, v0
	s_waitcnt lgkmcnt(3)
	v_add_f32_e32 v3, v3, v5
	ds_bpermute_b32 v5, v148, v3
	v_mul_f32_e32 v2, v4, v2
	ds_bpermute_b32 v0, v203, v0
	s_waitcnt lgkmcnt(2)
	v_mul_f32_e32 v4, v149, v6
	v_fma_f32 v6, -v48, v4, v18
	s_waitcnt lgkmcnt(1)
	v_add_f32_e32 v3, v3, v5
	v_fma_f32 v5, -v64, v4, v8
	v_mul_f32_e32 v8, v6, v6
	v_fmac_f32_e32 v8, v5, v5
	v_fma_f32 v10, -v32, v4, v22
	v_fmac_f32_e32 v8, v10, v10
	v_fma_f32 v4, -v16, v4, v24
	v_fmac_f32_e32 v8, v4, v4
	ds_bpermute_b32 v11, v144, v8
	v_fmamk_f32 v3, v3, 0x3c000000, v214
	v_rsq_f32_e32 v3, v3
	v_cvt_pk_bf16_f32 v2, v2, s0
	ds_write_b16 v7, v2 offset:192
	s_waitcnt lgkmcnt(1)
	v_add_f32_e32 v8, v8, v11
	ds_bpermute_b32 v11, v145, v8
	v_mul_f32_e32 v7, v13, v3
	v_mul_f32_e32 v0, v149, v0
	v_add_u32_e32 v2, v34, v200
	v_cvt_pk_bf16_f32 v7, v7, s0
	s_waitcnt lgkmcnt(0)
	v_add_f32_e32 v8, v8, v11
	ds_bpermute_b32 v11, v146, v8
	v_fma_f32 v13, -v49, v0, v19
	ds_write_b16 v2, v7
	v_mul_f32_e32 v7, v14, v3
	v_fma_f32 v9, -v65, v0, v9
	v_mul_f32_e32 v14, v13, v13
	v_fmac_f32_e32 v14, v9, v9
	v_fma_f32 v15, -v33, v0, v23
	v_fmac_f32_e32 v14, v15, v15
	v_fma_f32 v0, -v17, v0, v25
	s_waitcnt lgkmcnt(1)
	v_add_f32_e32 v8, v8, v11
	v_fmac_f32_e32 v14, v0, v0
	ds_bpermute_b32 v11, v147, v8
	ds_bpermute_b32 v16, v144, v14
	v_cvt_pk_bf16_f32 v7, v7, s0
	ds_write_b16 v2, v7 offset:64
	v_mul_f32_e32 v7, v26, v3
	v_cvt_pk_bf16_f32 v7, v7, s0
	ds_write_b16 v2, v7 offset:128
	s_waitcnt lgkmcnt(3)
	v_add_f32_e32 v7, v8, v11
	s_waitcnt lgkmcnt(2)
	v_add_f32_e32 v11, v14, v16
	ds_bpermute_b32 v8, v148, v7
	v_mul_f32_e32 v3, v12, v3
	ds_bpermute_b32 v12, v145, v11
	v_cvt_pk_bf16_f32 v3, v3, s0
	ds_write_b16 v2, v3 offset:192
	s_waitcnt lgkmcnt(2)
	v_add_f32_e32 v7, v7, v8
	v_fmamk_f32 v7, v7, 0x3c000000, v214
	s_waitcnt lgkmcnt(1)
	v_add_f32_e32 v8, v11, v12
	ds_bpermute_b32 v11, v146, v8
	v_rsq_f32_e32 v7, v7
	v_add_u32_e32 v2, v34, v202
	v_mul_f32_e32 v3, v5, v7
	s_waitcnt lgkmcnt(0)
	v_add_f32_e32 v5, v8, v11
	ds_bpermute_b32 v8, v147, v5
	v_cvt_pk_bf16_f32 v3, v3, s0
	ds_write_b16 v2, v3
	v_mul_f32_e32 v3, v6, v7
	v_cvt_pk_bf16_f32 v3, v3, s0
	ds_write_b16 v2, v3 offset:64
	s_waitcnt lgkmcnt(2)
	v_add_f32_e32 v3, v5, v8
	ds_bpermute_b32 v5, v148, v3
	v_mul_f32_e32 v4, v4, v7
	v_mul_f32_e32 v6, v10, v7
	v_cvt_pk_bf16_f32 v4, v4, s0
	v_cvt_pk_bf16_f32 v6, v6, s0
	s_waitcnt lgkmcnt(0)
	v_add_f32_e32 v3, v3, v5
	v_fmamk_f32 v3, v3, 0x3c000000, v214
	v_rsq_f32_e32 v3, v3
	ds_write_b16 v2, v4 offset:192
	ds_write_b16 v2, v6 offset:128
	v_add_u32_e32 v2, v34, v204
	v_mul_f32_e32 v4, v9, v3
	v_cvt_pk_bf16_f32 v4, v4, s0
	ds_write_b16 v2, v4
	v_mul_f32_e32 v4, v13, v3
	v_cvt_pk_bf16_f32 v4, v4, s0
	ds_write_b16 v2, v4 offset:64
	v_mul_f32_e32 v4, v15, v3
	v_mul_f32_e32 v0, v0, v3
	v_cvt_pk_bf16_f32 v4, v4, s0
	v_cvt_pk_bf16_f32 v0, v0, s0
	ds_write_b16 v2, v4 offset:128
	ds_write_b16 v2, v0 offset:192
	v_add_u32_e32 v0, s3, v122
	s_waitcnt lgkmcnt(0)
	v_add_u32_e32 v2, v0, v205
	ds_read_b128 v[2:5], v2
	v_add_u32_e32 v6, v0, v206
	ds_read_b128 v[6:9], v6
	v_lshl_add_u64 v[10:11], s[26:27], 0, v[122:123]
	v_lshl_add_u64 v[12:13], v[10:11], 0, v[124:125]
	s_waitcnt lgkmcnt(1)
	global_store_dwordx4 v[12:13], v[2:5], off nt
	v_lshl_add_u64 v[12:13], v[10:11], 0, v[128:129]
	s_nop 0
	v_lshl_add_u64 v[2:3], v[10:11], 0, v[126:127]
	s_waitcnt lgkmcnt(0)
	global_store_dwordx4 v[2:3], v[6:9], off nt
	v_add_u32_e32 v2, v0, v207
	ds_read_b128 v[2:5], v2
	v_add_u32_e32 v6, v0, v208
	ds_read_b128 v[6:9], v6
	s_waitcnt lgkmcnt(1)
	global_store_dwordx4 v[12:13], v[2:5], off nt
	s_nop 1
	v_lshl_add_u64 v[2:3], v[10:11], 0, v[130:131]
	s_waitcnt lgkmcnt(0)
	global_store_dwordx4 v[2:3], v[6:9], off nt
	v_add_u32_e32 v2, v0, v209
	ds_read_b128 v[2:5], v2
	v_add_u32_e32 v6, v0, v210
	ds_read_b128 v[6:9], v6
	v_lshl_add_u64 v[12:13], v[10:11], 0, v[132:133]
	s_waitcnt lgkmcnt(1)
	global_store_dwordx4 v[12:13], v[2:5], off nt
	v_lshl_add_u64 v[12:13], v[10:11], 0, v[136:137]
	s_nop 0
	v_lshl_add_u64 v[2:3], v[10:11], 0, v[134:135]
	s_waitcnt lgkmcnt(0)
	global_store_dwordx4 v[2:3], v[6:9], off nt
	v_add_u32_e32 v2, v0, v211
	ds_read_b128 v[2:5], v2
	v_add_u32_e32 v0, v0, v212
	ds_read_b128 v[6:9], v0
	s_waitcnt lgkmcnt(1)
	global_store_dwordx4 v[12:13], v[2:5], off nt
	s_nop 1
	v_lshl_add_u64 v[2:3], v[10:11], 0, v[138:139]
	s_waitcnt lgkmcnt(0)
	global_store_dwordx4 v[2:3], v[6:9], off nt
	s_branch .LBB0_465
